# P6 order swap selected by bid bit 3 (every XCD has half of its workgroups in each order) instead of bid bit 0 (whole XCDs)
# baseline (speedup 1.0000x reference)
; __global__ void __launch_bounds__(512, 2) fwd_mega(Params P) {
;     ...
;     { EpiUp E{(bf16_t*)(ws + OFF_FFB)}; run_gemm(glds, (const bf16_t*)(ws + OFF_H1B), (const bf16_t*)(ws + OFF_WUP), 4096, DM, E, wid_s); }
;     { EpiGate E{(bf16_t*)(ws + OFF_PG), P.in[18]}; run_gemm(glds, (const bf16_t*)(ws + OFF_H1B), (const bf16_t*)(ws + OFF_WG), DM, DM, E, wid_s); }
.Lp6_up_entry:
	s_add_u32 s4, s80, 0x4800000
	v_readlane_b32 s0, v255, 31
	s_addc_u32 s5, s81, 0
	s_lshl_b32 s0, s0, 5
	s_and_b32 s36, s0, 0x60
	s_lshl_b32 s37, s36, 7
	s_cmpk_gt_i32 s33, 0x3ff
	s_waitcnt lgkmcnt(0)
	s_barrier
	v_mbcnt_lo_u32_b32 v8, -1, 0
	v_mbcnt_hi_u32_b32 v8, -1, v8
	s_cbranch_scc1 .LBB0_830
	s_cmp_eq_u32 s98, 0
	s_cbranch_scc0 .Lp6_up_go
	s_bitcmp1_b32 s33, 3
	s_cbranch_scc0 .Lp6_up_go
	s_mov_b32 s98, 1
	s_branch .LBB0_830
